# attention epilogue: 13 subln_g vector loads in flight together; combine row loop: 24 gather loads issued together
# speedup vs baseline: 1.0135x; 1.0046x over previous
; DI float shx(float v, int o) { int lane = otid() & 63; return __builtin_bit_cast(float, __builtin_amdgcn_ds_bpermute((lane ^ o) << 2, __builtin_bit_cast(int, v))); }
; DI void attn_item(const P& p, int l, int b, int h, int qpos0, int key0, int nkeys, int out_row0, unsigned char* lds,
;                   float lam, float lam_init) {
;     ...
;   float l0 = lsum[0] + shx(lsum[0], 32), l1 = lsum[1] + shx(lsum[1], 32);
;   float i0 = 1.f / l0, i1 = lam / l1;
;   float ssq = 0.f;
; #pragma unroll
;   for (int vt = 0; vt < 4; ++vt)
; #pragma unroll
;     for (int i = 0; i < 16; ++i) { float o = O[0][vt][i] * i0 - O[1][vt][i] * i1; O[0][vt][i] = o; ssq += o * o; }
;   ssq += shx(ssq, 32);
;   float rn = rsqrtf(ssq * (1.f / 128.f) + 1e-5f) * (1.f - lam_init);
.LBB0_305:
	v_mov_b32_e32 v130, v215
	v_mov_b32_e32 v131, v215
	v_lshlrev_b32_e32 v130, 2, v130
	v_bitop3_b32 v130, v130, s76, v220 bitop3:0x6c
	ds_bpermute_b32 v130, v130, v180
	s_lshl_b32 s54, s13, 1
	v_lshlrev_b32_e32 v131, 2, v131
	v_bitop3_b32 v131, v131, s76, v220 bitop3:0x6c
	s_waitcnt lgkmcnt(0)
	v_add_f32_e32 v130, v180, v130
	v_div_scale_f32 v132, s[0:1], v130, v130, 1.0
	v_rcp_f32_e32 v133, v132
	ds_bpermute_b32 v131, v131, v181
	v_lshlrev_b32_e32 v178, 3, v185
	v_fma_f32 v134, -v132, v133, 1.0
	v_fmac_f32_e32 v133, v134, v133
	v_div_scale_f32 v134, vcc, 1.0, v130, 1.0
	v_mul_f32_e32 v135, v134, v133
	v_fma_f32 v136, -v132, v135, v134
	v_fmac_f32_e32 v135, v136, v133
	v_fma_f32 v132, -v132, v135, v134
	s_waitcnt lgkmcnt(0)
	v_add_f32_e32 v131, v181, v131
	v_div_fmas_f32 v132, v132, v133, v135
	v_div_fixup_f32 v136, v132, v130, 1.0
	v_div_scale_f32 v130, s[0:1], v131, v131, v182
	v_rcp_f32_e32 v132, v130
	v_readlane_b32 s0, v253, 24
	v_readlane_b32 s1, v253, 25
	v_fma_f32 v133, -v130, v132, 1.0
	v_fmac_f32_e32 v132, v133, v132
	v_div_scale_f32 v133, vcc, v182, v131, v182
	v_mul_f32_e32 v134, v133, v132
	v_fma_f32 v135, -v130, v134, v133
	v_fmac_f32_e32 v134, v135, v132
	v_fma_f32 v130, -v130, v134, v133
	v_div_fmas_f32 v130, v130, v132, v134
	v_div_fixup_f32 v138, v130, v131, v182
	v_pk_mul_f32 v[14:15], v[14:15], v[138:139] op_sel_hi:[1,0]
	v_pk_mul_f32 v[98:99], v[98:99], v[138:139] op_sel_hi:[1,0]
	v_pk_fma_f32 v[130:131], v[30:31], v[136:137], v[14:15] op_sel_hi:[1,0,1] neg_lo:[0,0,1] neg_hi:[0,0,1]
	v_pk_mul_f32 v[14:15], v[16:17], v[138:139] op_sel_hi:[1,0]
	v_pk_mul_f32 v[2:3], v[2:3], v[138:139] op_sel_hi:[1,0]
	v_pk_fma_f32 v[30:31], v[32:33], v[136:137], v[14:15] op_sel_hi:[1,0,1] neg_lo:[0,0,1] neg_hi:[0,0,1]
	v_mov_b32_e32 v14, v215
	v_pk_mul_f32 v[4:5], v[4:5], v[138:139] op_sel_hi:[1,0]
	v_lshlrev_b32_e32 v14, 2, v14
	v_bitop3_b32 v137, v14, s76, v220 bitop3:0x6c
	v_add3_u32 v14, v186, s12, v184
	v_ashrrev_i32_e32 v15, 31, v14
	v_lshlrev_b64 v[14:15], 10, v[14:15]
	v_lshl_add_u64 v[14:15], s[0:1], 0, v[14:15]
	v_lshl_add_u64 v[32:33], v[14:15], 0, s[54:55]
	v_pk_mul_f32 v[14:15], v[100:101], v[138:139] op_sel_hi:[1,0]
	v_pk_fma_f32 v[114:115], v[114:115], v[136:137], v[98:99] op_sel_hi:[1,0,1] neg_lo:[0,0,1] neg_hi:[0,0,1]
	v_pk_fma_f32 v[18:19], v[18:19], v[136:137], v[2:3] op_sel_hi:[1,0,1] neg_lo:[0,0,1] neg_hi:[0,0,1]
	v_pk_mul_f32 v[2:3], v[8:9], v[138:139] op_sel_hi:[1,0]
	v_pk_fma_f32 v[116:117], v[116:117], v[136:137], v[14:15] op_sel_hi:[1,0,1] neg_lo:[0,0,1] neg_hi:[0,0,1]
	v_pk_mul_f32 v[142:143], v[114:115], v[114:115]
	v_pk_mul_f32 v[98:99], v[104:105], v[138:139] op_sel_hi:[1,0]
	v_pk_fma_f32 v[20:21], v[20:21], v[136:137], v[4:5] op_sel_hi:[1,0,1] neg_lo:[0,0,1] neg_hi:[0,0,1]
	v_pk_fma_f32 v[4:5], v[24:25], v[136:137], v[2:3] op_sel_hi:[1,0,1] neg_lo:[0,0,1] neg_hi:[0,0,1]
	v_pk_mul_f32 v[2:3], v[6:7], v[138:139] op_sel_hi:[1,0]
	v_pk_mul_f32 v[6:7], v[10:11], v[138:139] op_sel_hi:[1,0]
	v_pk_mul_f32 v[140:141], v[116:117], v[116:117]
	global_load_dwordx4 v[14:17], v1, s[8:9]
	v_pk_fma_f32 v[120:121], v[120:121], v[136:137], v[98:99] op_sel_hi:[1,0,1] neg_lo:[0,0,1] neg_hi:[0,0,1]
	v_pk_mul_f32 v[98:99], v[102:103], v[138:139] op_sel_hi:[1,0]
	v_pk_fma_f32 v[6:7], v[26:27], v[136:137], v[6:7] op_sel_hi:[1,0,1] neg_lo:[0,0,1] neg_hi:[0,0,1]
	v_add_f32_e32 v26, v142, v143
	v_pk_fma_f32 v[118:119], v[118:119], v[136:137], v[98:99] op_sel_hi:[1,0,1] neg_lo:[0,0,1] neg_hi:[0,0,1]
	v_add_f32_e32 v26, v140, v26
	v_pk_mul_f32 v[146:147], v[118:119], v[118:119]
	v_add_f32_e32 v26, v141, v26
	v_pk_mul_f32 v[98:99], v[108:109], v[138:139] op_sel_hi:[1,0]
	v_add_f32_e32 v26, v146, v26
	v_pk_mul_f32 v[144:145], v[120:121], v[120:121]
	v_pk_fma_f32 v[102:103], v[124:125], v[136:137], v[98:99] op_sel_hi:[1,0,1] neg_lo:[0,0,1] neg_hi:[0,0,1]
	v_pk_mul_f32 v[98:99], v[106:107], v[138:139] op_sel_hi:[1,0]
	v_add_f32_e32 v26, v147, v26
	v_pk_fma_f32 v[106:107], v[122:123], v[136:137], v[98:99] op_sel_hi:[1,0,1] neg_lo:[0,0,1] neg_hi:[0,0,1]
	v_add_f32_e32 v26, v144, v26
	v_pk_mul_f32 v[122:123], v[106:107], v[106:107]
	v_add_f32_e32 v26, v145, v26
	v_add_f32_e32 v26, v122, v26
	v_pk_mul_f32 v[108:109], v[102:103], v[102:103]
	v_pk_mul_f32 v[100:101], v[110:111], v[138:139] op_sel_hi:[1,0]
	v_add_f32_e32 v26, v123, v26
	v_pk_fma_f32 v[104:105], v[126:127], v[136:137], v[100:101] op_sel_hi:[1,0,1] neg_lo:[0,0,1] neg_hi:[0,0,1]
	v_add_f32_e32 v26, v108, v26
	v_pk_mul_f32 v[98:99], v[112:113], v[138:139] op_sel_hi:[1,0]
	v_pk_mul_f32 v[110:111], v[104:105], v[104:105]
	v_add_f32_e32 v26, v109, v26
	v_pk_fma_f32 v[98:99], v[128:129], v[136:137], v[98:99] op_sel_hi:[1,0,1] neg_lo:[0,0,1] neg_hi:[0,0,1]
	v_add_f32_e32 v26, v110, v26
	v_pk_mul_f32 v[112:113], v[98:99], v[98:99]
	v_pk_mul_f32 v[66:67], v[66:67], v[138:139] op_sel_hi:[1,0]
	v_add_f32_e32 v26, v111, v26
	v_pk_fma_f32 v[100:101], v[82:83], v[136:137], v[66:67] op_sel_hi:[1,0,1] neg_lo:[0,0,1] neg_hi:[0,0,1]
	v_add_f32_e32 v26, v112, v26
	v_pk_mul_f32 v[68:69], v[68:69], v[138:139] op_sel_hi:[1,0]
	v_pk_mul_f32 v[126:127], v[100:101], v[100:101]
	v_add_f32_e32 v26, v113, v26
	v_pk_fma_f32 v[84:85], v[84:85], v[136:137], v[68:69] op_sel_hi:[1,0,1] neg_lo:[0,0,1] neg_hi:[0,0,1]
	v_pk_mul_f32 v[66:67], v[72:73], v[138:139] op_sel_hi:[1,0]
	v_add_f32_e32 v26, v126, v26
	v_pk_mul_f32 v[124:125], v[84:85], v[84:85]
	v_pk_fma_f32 v[82:83], v[88:89], v[136:137], v[66:67] op_sel_hi:[1,0,1] neg_lo:[0,0,1] neg_hi:[0,0,1]
	v_pk_mul_f32 v[66:67], v[70:71], v[138:139] op_sel_hi:[1,0]
	v_add_f32_e32 v26, v127, v26
	v_pk_fma_f32 v[86:87], v[86:87], v[136:137], v[66:67] op_sel_hi:[1,0,1] neg_lo:[0,0,1] neg_hi:[0,0,1]
; DI unsigned pack2(float a, float b) { fl2_t f = {a, b}; bf2_t r = __builtin_convertvector(f, bf2_t); return __builtin_bit_cast(unsigned, r); }
; DI float shx(float v, int o) { int lane = otid() & 63; return __builtin_bit_cast(float, __builtin_amdgcn_ds_bpermute((lane ^ o) << 2, __builtin_bit_cast(int, v))); }
; DI void attn_item(const P& p, int l, int b, int h, int qpos0, int key0, int nkeys, int out_row0, unsigned char* lds,
;                   float lam, float lam_init) {
;     ...
;   float ssq = 0.f;
; #pragma unroll
;   for (int vt = 0; vt < 4; ++vt)
; #pragma unroll
;     for (int i = 0; i < 16; ++i) { float o = O[0][vt][i] * i0 - O[1][vt][i] * i1; O[0][vt][i] = o; ssq += o * o; }
;   ssq += shx(ssq, 32);
;   float rn = rsqrtf(ssq * (1.f / 128.f) + 1e-5f) * (1.f - lam_init);
;   const float* sg = p.in[I_SUBG] + l * 128;
;   u16* OO = (u16*)(p.ws + O_O) + (size_t)(out_row0 + w * 32 + r) * 512 + h * 128;
; #pragma unroll
;   for (int vt = 0; vt < 4; ++vt)
; #pragma unroll
;     for (int g4 = 0; g4 < 4; ++g4) {
;       int e0 = 32 * vt + 8 * g4 + 4 * hh;
;       float4 gv = *(const float4*)(sg + e0);
;       *(uint2*)(OO + e0) = make_uint2(pack2(O[0][vt][4 * g4] * rn * gv.x, O[0][vt][4 * g4 + 1] * rn * gv.y),
;                                       pack2(O[0][vt][4 * g4 + 2] * rn * gv.z, O[0][vt][4 * g4 + 3] * rn * gv.w));
;     }
	v_add_f32_e32 v26, v124, v26
	v_pk_mul_f32 v[128:129], v[86:87], v[86:87]
	v_add_f32_e32 v26, v125, v26
	v_pk_mul_f32 v[66:67], v[76:77], v[138:139] op_sel_hi:[1,0]
	v_add_f32_e32 v26, v128, v26
	v_pk_mul_f32 v[88:89], v[82:83], v[82:83]
	v_pk_fma_f32 v[70:71], v[92:93], v[136:137], v[66:67] op_sel_hi:[1,0,1] neg_lo:[0,0,1] neg_hi:[0,0,1]
	v_pk_mul_f32 v[66:67], v[74:75], v[138:139] op_sel_hi:[1,0]
	v_add_f32_e32 v26, v129, v26
	v_pk_fma_f32 v[74:75], v[90:91], v[136:137], v[66:67] op_sel_hi:[1,0,1] neg_lo:[0,0,1] neg_hi:[0,0,1]
	v_add_f32_e32 v26, v88, v26
	v_pk_mul_f32 v[90:91], v[74:75], v[74:75]
	v_add_f32_e32 v26, v89, v26
	v_add_f32_e32 v26, v90, v26
	v_pk_mul_f32 v[76:77], v[70:71], v[70:71]
	v_pk_mul_f32 v[68:69], v[78:79], v[138:139] op_sel_hi:[1,0]
	v_add_f32_e32 v26, v91, v26
	v_pk_fma_f32 v[72:73], v[94:95], v[136:137], v[68:69] op_sel_hi:[1,0,1] neg_lo:[0,0,1] neg_hi:[0,0,1]
	v_add_f32_e32 v26, v76, v26
	v_pk_mul_f32 v[66:67], v[80:81], v[138:139] op_sel_hi:[1,0]
	v_pk_mul_f32 v[78:79], v[72:73], v[72:73]
	v_add_f32_e32 v26, v77, v26
	v_pk_fma_f32 v[66:67], v[96:97], v[136:137], v[66:67] op_sel_hi:[1,0,1] neg_lo:[0,0,1] neg_hi:[0,0,1]
	v_add_f32_e32 v26, v78, v26
	v_pk_mul_f32 v[80:81], v[66:67], v[66:67]
	v_pk_mul_f32 v[34:35], v[34:35], v[138:139] op_sel_hi:[1,0]
	v_add_f32_e32 v26, v79, v26
	v_pk_fma_f32 v[68:69], v[50:51], v[136:137], v[34:35] op_sel_hi:[1,0,1] neg_lo:[0,0,1] neg_hi:[0,0,1]
	v_add_f32_e32 v26, v80, v26
	v_pk_mul_f32 v[36:37], v[36:37], v[138:139] op_sel_hi:[1,0]
	v_pk_mul_f32 v[94:95], v[68:69], v[68:69]
	v_add_f32_e32 v26, v81, v26
	v_pk_fma_f32 v[52:53], v[52:53], v[136:137], v[36:37] op_sel_hi:[1,0,1] neg_lo:[0,0,1] neg_hi:[0,0,1]
	v_pk_mul_f32 v[34:35], v[40:41], v[138:139] op_sel_hi:[1,0]
	v_add_f32_e32 v26, v94, v26
	v_pk_mul_f32 v[92:93], v[52:53], v[52:53]
	v_pk_fma_f32 v[40:41], v[56:57], v[136:137], v[34:35] op_sel_hi:[1,0,1] neg_lo:[0,0,1] neg_hi:[0,0,1]
	v_pk_mul_f32 v[34:35], v[38:39], v[138:139] op_sel_hi:[1,0]
	v_add_f32_e32 v26, v95, v26
	v_pk_fma_f32 v[50:51], v[54:55], v[136:137], v[34:35] op_sel_hi:[1,0,1] neg_lo:[0,0,1] neg_hi:[0,0,1]
	v_add_f32_e32 v26, v92, v26
	v_pk_mul_f32 v[54:55], v[50:51], v[50:51]
	v_add_f32_e32 v26, v93, v26
	v_pk_mul_f32 v[34:35], v[44:45], v[138:139] op_sel_hi:[1,0]
	v_add_f32_e32 v26, v54, v26
	v_pk_mul_f32 v[56:57], v[40:41], v[40:41]
	v_pk_fma_f32 v[36:37], v[60:61], v[136:137], v[34:35] op_sel_hi:[1,0,1] neg_lo:[0,0,1] neg_hi:[0,0,1]
	v_pk_mul_f32 v[34:35], v[42:43], v[138:139] op_sel_hi:[1,0]
	v_add_f32_e32 v26, v55, v26
	v_pk_fma_f32 v[42:43], v[58:59], v[136:137], v[34:35] op_sel_hi:[1,0,1] neg_lo:[0,0,1] neg_hi:[0,0,1]
	v_add_f32_e32 v26, v56, v26
	v_pk_mul_f32 v[58:59], v[42:43], v[42:43]
	v_add_f32_e32 v26, v57, v26
	v_add_f32_e32 v26, v58, v26
	v_pk_mul_f32 v[44:45], v[36:37], v[36:37]
	v_pk_mul_f32 v[38:39], v[46:47], v[138:139] op_sel_hi:[1,0]
	v_add_f32_e32 v26, v59, v26
	v_pk_fma_f32 v[38:39], v[62:63], v[136:137], v[38:39] op_sel_hi:[1,0,1] neg_lo:[0,0,1] neg_hi:[0,0,1]
	v_add_f32_e32 v26, v44, v26
	v_pk_mul_f32 v[34:35], v[48:49], v[138:139] op_sel_hi:[1,0]
	v_pk_mul_f32 v[46:47], v[38:39], v[38:39]
	v_add_f32_e32 v26, v45, v26
	v_pk_fma_f32 v[34:35], v[64:65], v[136:137], v[34:35] op_sel_hi:[1,0,1] neg_lo:[0,0,1] neg_hi:[0,0,1]
	v_add_f32_e32 v26, v46, v26
	v_pk_mul_f32 v[48:49], v[34:35], v[34:35]
	v_add_f32_e32 v26, v47, v26
	v_add_f32_e32 v26, v48, v26
	v_pk_mul_f32 v[62:63], v[18:19], v[18:19]
	v_add_f32_e32 v26, v49, v26
	v_add_f32_e32 v26, v62, v26
	v_pk_mul_f32 v[60:61], v[20:21], v[20:21]
	v_add_f32_e32 v26, v63, v26
	v_pk_fma_f32 v[8:9], v[22:23], v[136:137], v[2:3] op_sel_hi:[1,0,1] neg_lo:[0,0,1] neg_hi:[0,0,1]
	v_add_f32_e32 v26, v60, v26
	v_pk_mul_f32 v[22:23], v[8:9], v[8:9]
	v_add_f32_e32 v26, v61, v26
	v_add_f32_e32 v22, v22, v26
	v_pk_mul_f32 v[24:25], v[4:5], v[4:5]
	v_add_f32_e32 v22, v23, v22
	v_add_f32_e32 v22, v24, v22
	v_pk_mul_f32 v[2:3], v[12:13], v[138:139] op_sel_hi:[1,0]
	v_pk_mul_f32 v[10:11], v[6:7], v[6:7]
	v_add_f32_e32 v22, v25, v22
	v_pk_fma_f32 v[2:3], v[28:29], v[136:137], v[2:3] op_sel_hi:[1,0,1] neg_lo:[0,0,1] neg_hi:[0,0,1]
	v_add_f32_e32 v10, v10, v22
	v_pk_mul_f32 v[12:13], v[2:3], v[2:3]
	v_add_f32_e32 v10, v11, v10
	v_add_f32_e32 v10, v12, v10
	v_pk_mul_f32 v[132:133], v[130:131], v[130:131]
	v_add_f32_e32 v10, v13, v10
	v_add_f32_e32 v10, v132, v10
	v_pk_mul_f32 v[134:135], v[30:31], v[30:31]
	v_add_f32_e32 v10, v133, v10
	v_add_f32_e32 v10, v134, v10
	v_add_f32_e32 v10, v135, v10
	ds_bpermute_b32 v11, v137, v10
	v_lshl_add_u64 v[32:33], v[32:33], 0, v[178:179]
	s_waitcnt lgkmcnt(0)
	v_add_f32_e32 v10, v10, v11
	v_fmamk_f32 v10, v10, 0x3c000000, v217
	v_cmp_gt_f32_e32 vcc, s77, v10
	v_mul_f32_e32 v11, 0x4b800000, v10
	s_nop 0
	v_cndmask_b32_e32 v10, v10, v11, vcc
	v_rsq_f32_e32 v10, v10
	s_nop 0
	v_mul_f32_e32 v11, 0x45800000, v10
	v_cndmask_b32_e32 v10, v10, v11, vcc
	v_mul_f32_e32 v10, v183, v10
	v_pk_mul_f32 v[12:13], v[114:115], v[10:11] op_sel_hi:[1,0]
	v_pk_mul_f32 v[8:9], v[8:9], v[10:11] op_sel_hi:[1,0]
	s_waitcnt vmcnt(0)
	v_pk_mul_f32 v[12:13], v[14:15], v[12:13]
	v_pk_mul_f32 v[14:15], v[116:117], v[10:11] op_sel_hi:[1,0]
	v_cvt_pk_bf16_f32 v12, v12, v13
	v_pk_mul_f32 v[14:15], v[16:17], v[14:15]
	v_pk_mul_f32 v[16:17], v[118:119], v[10:11] op_sel_hi:[1,0]
	v_cvt_pk_bf16_f32 v13, v14, v15
	global_store_dwordx2 v[32:33], v[12:13], off
	global_load_dwordx4 v[148:151], v1, s[8:9] offset:32
	global_load_dwordx4 v[152:155], v1, s[8:9] offset:64
	global_load_dwordx4 v[156:159], v1, s[8:9] offset:96
	global_load_dwordx4 v[184:187], v1, s[8:9] offset:128
	global_load_dwordx4 v[194:197], v1, s[8:9] offset:160
	global_load_dwordx4 v[198:201], v1, s[8:9] offset:192
	global_load_dwordx4 v[202:205], v1, s[8:9] offset:224
	global_load_dwordx4 v[206:209], v1, s[8:9] offset:256
	global_load_dwordx4 v[226:229], v1, s[8:9] offset:288
	global_load_dwordx4 v[232:235], v1, s[8:9] offset:320
	global_load_dwordx4 v[236:239], v1, s[8:9] offset:352
	global_load_dwordx4 v[240:243], v1, s[8:9] offset:384
	global_load_dwordx4 v[244:247], v1, s[8:9] offset:416
	s_waitcnt vmcnt(12)
; DI unsigned pack2(float a, float b) { fl2_t f = {a, b}; bf2_t r = __builtin_convertvector(f, bf2_t); return __builtin_bit_cast(unsigned, r); }
; DI void attn_item(const P& p, int l, int b, int h, int qpos0, int key0, int nkeys, int out_row0, unsigned char* lds,
;                   float lam, float lam_init) {
;     ...
; #pragma unroll
;   for (int vt = 0; vt < 4; ++vt)
; #pragma unroll
;     for (int g4 = 0; g4 < 4; ++g4) {
;       int e0 = 32 * vt + 8 * g4 + 4 * hh;
;       float4 gv = *(const float4*)(sg + e0);
;       *(uint2*)(OO + e0) = make_uint2(pack2(O[0][vt][4 * g4] * rn * gv.x, O[0][vt][4 * g4 + 1] * rn * gv.y),
;                                       pack2(O[0][vt][4 * g4 + 2] * rn * gv.z, O[0][vt][4 * g4 + 3] * rn * gv.w));
;     }
	v_mov_b64_e32 v[12:13], v[148:149]
	v_mov_b64_e32 v[14:15], v[150:151]
	v_pk_mul_f32 v[4:5], v[4:5], v[10:11] op_sel_hi:[1,0]
	v_pk_mul_f32 v[2:3], v[2:3], v[10:11] op_sel_hi:[1,0]
	v_pk_mul_f32 v[12:13], v[12:13], v[16:17]
	v_pk_mul_f32 v[16:17], v[120:121], v[10:11] op_sel_hi:[1,0]
	v_cvt_pk_bf16_f32 v12, v12, v13
	v_pk_mul_f32 v[14:15], v[14:15], v[16:17]
	v_pk_mul_f32 v[16:17], v[106:107], v[10:11] op_sel_hi:[1,0]
	v_cvt_pk_bf16_f32 v13, v14, v15
	global_store_dwordx2 v[32:33], v[12:13], off offset:16
	s_waitcnt vmcnt(12)
	v_mov_b64_e32 v[12:13], v[152:153]
	v_mov_b64_e32 v[14:15], v[154:155]
	v_pk_mul_f32 v[12:13], v[12:13], v[16:17]
	v_pk_mul_f32 v[16:17], v[102:103], v[10:11] op_sel_hi:[1,0]
	v_cvt_pk_bf16_f32 v12, v12, v13
	v_pk_mul_f32 v[14:15], v[14:15], v[16:17]
	v_pk_mul_f32 v[16:17], v[104:105], v[10:11] op_sel_hi:[1,0]
	v_cvt_pk_bf16_f32 v13, v14, v15
	global_store_dwordx2 v[32:33], v[12:13], off offset:32
	s_waitcnt vmcnt(12)
	v_mov_b64_e32 v[12:13], v[156:157]
	v_mov_b64_e32 v[14:15], v[158:159]
	v_pk_mul_f32 v[12:13], v[12:13], v[16:17]
	v_pk_mul_f32 v[16:17], v[98:99], v[10:11] op_sel_hi:[1,0]
	v_cvt_pk_bf16_f32 v12, v12, v13
	v_pk_mul_f32 v[14:15], v[14:15], v[16:17]
	v_pk_mul_f32 v[16:17], v[100:101], v[10:11] op_sel_hi:[1,0]
	v_cvt_pk_bf16_f32 v13, v14, v15
	global_store_dwordx2 v[32:33], v[12:13], off offset:48
	s_waitcnt vmcnt(12)
	v_mov_b64_e32 v[12:13], v[184:185]
	v_mov_b64_e32 v[14:15], v[186:187]
	v_pk_mul_f32 v[12:13], v[12:13], v[16:17]
	v_pk_mul_f32 v[16:17], v[84:85], v[10:11] op_sel_hi:[1,0]
	v_cvt_pk_bf16_f32 v12, v12, v13
	v_pk_mul_f32 v[14:15], v[14:15], v[16:17]
	v_pk_mul_f32 v[16:17], v[86:87], v[10:11] op_sel_hi:[1,0]
	v_cvt_pk_bf16_f32 v13, v14, v15
	global_store_dwordx2 v[32:33], v[12:13], off offset:64
	s_waitcnt vmcnt(12)
	v_mov_b64_e32 v[12:13], v[194:195]
	v_mov_b64_e32 v[14:15], v[196:197]
	v_pk_mul_f32 v[12:13], v[12:13], v[16:17]
	v_pk_mul_f32 v[16:17], v[82:83], v[10:11] op_sel_hi:[1,0]
	v_cvt_pk_bf16_f32 v12, v12, v13
	v_pk_mul_f32 v[14:15], v[14:15], v[16:17]
	v_pk_mul_f32 v[16:17], v[74:75], v[10:11] op_sel_hi:[1,0]
	v_cvt_pk_bf16_f32 v13, v14, v15
	global_store_dwordx2 v[32:33], v[12:13], off offset:80
	s_waitcnt vmcnt(12)
	v_mov_b64_e32 v[12:13], v[198:199]
	v_mov_b64_e32 v[14:15], v[200:201]
	v_pk_mul_f32 v[12:13], v[12:13], v[16:17]
	v_pk_mul_f32 v[16:17], v[70:71], v[10:11] op_sel_hi:[1,0]
	v_cvt_pk_bf16_f32 v12, v12, v13
	v_pk_mul_f32 v[14:15], v[14:15], v[16:17]
	v_pk_mul_f32 v[16:17], v[72:73], v[10:11] op_sel_hi:[1,0]
	v_cvt_pk_bf16_f32 v13, v14, v15
	global_store_dwordx2 v[32:33], v[12:13], off offset:96
	s_waitcnt vmcnt(12)
	v_mov_b64_e32 v[12:13], v[202:203]
	v_mov_b64_e32 v[14:15], v[204:205]
	v_pk_mul_f32 v[12:13], v[12:13], v[16:17]
	v_pk_mul_f32 v[16:17], v[66:67], v[10:11] op_sel_hi:[1,0]
	v_cvt_pk_bf16_f32 v12, v12, v13
	v_pk_mul_f32 v[14:15], v[14:15], v[16:17]
	v_pk_mul_f32 v[16:17], v[68:69], v[10:11] op_sel_hi:[1,0]
	v_cvt_pk_bf16_f32 v13, v14, v15
	global_store_dwordx2 v[32:33], v[12:13], off offset:112
	s_waitcnt vmcnt(12)
	v_mov_b64_e32 v[12:13], v[206:207]
	v_mov_b64_e32 v[14:15], v[208:209]
	v_pk_mul_f32 v[12:13], v[12:13], v[16:17]
	v_pk_mul_f32 v[16:17], v[52:53], v[10:11] op_sel_hi:[1,0]
	v_cvt_pk_bf16_f32 v12, v12, v13
	v_pk_mul_f32 v[14:15], v[14:15], v[16:17]
	v_pk_mul_f32 v[16:17], v[50:51], v[10:11] op_sel_hi:[1,0]
	v_cvt_pk_bf16_f32 v13, v14, v15
	global_store_dwordx2 v[32:33], v[12:13], off offset:128
	s_waitcnt vmcnt(12)
	v_mov_b64_e32 v[12:13], v[226:227]
	v_mov_b64_e32 v[14:15], v[228:229]
	v_pk_mul_f32 v[12:13], v[12:13], v[16:17]
	v_pk_mul_f32 v[16:17], v[40:41], v[10:11] op_sel_hi:[1,0]
	v_cvt_pk_bf16_f32 v12, v12, v13
	v_pk_mul_f32 v[14:15], v[14:15], v[16:17]
	v_pk_mul_f32 v[16:17], v[42:43], v[10:11] op_sel_hi:[1,0]
	v_cvt_pk_bf16_f32 v13, v14, v15
	global_store_dwordx2 v[32:33], v[12:13], off offset:144
	s_waitcnt vmcnt(12)
	v_mov_b64_e32 v[12:13], v[232:233]
	v_mov_b64_e32 v[14:15], v[234:235]
	v_pk_mul_f32 v[12:13], v[12:13], v[16:17]
	v_pk_mul_f32 v[16:17], v[36:37], v[10:11] op_sel_hi:[1,0]
	v_cvt_pk_bf16_f32 v12, v12, v13
	v_pk_mul_f32 v[14:15], v[14:15], v[16:17]
	v_pk_mul_f32 v[16:17], v[38:39], v[10:11] op_sel_hi:[1,0]
	v_cvt_pk_bf16_f32 v13, v14, v15
	global_store_dwordx2 v[32:33], v[12:13], off offset:160
	s_waitcnt vmcnt(12)
	v_mov_b64_e32 v[12:13], v[236:237]
	v_mov_b64_e32 v[14:15], v[238:239]
	v_pk_mul_f32 v[12:13], v[12:13], v[16:17]
	v_pk_mul_f32 v[16:17], v[34:35], v[10:11] op_sel_hi:[1,0]
	v_cvt_pk_bf16_f32 v12, v12, v13
	v_pk_mul_f32 v[14:15], v[14:15], v[16:17]
	v_pk_mul_f32 v[16:17], v[18:19], v[10:11] op_sel_hi:[1,0]
	v_cvt_pk_bf16_f32 v13, v14, v15
	global_store_dwordx2 v[32:33], v[12:13], off offset:176
	s_waitcnt vmcnt(12)
	v_mov_b64_e32 v[12:13], v[240:241]
	v_mov_b64_e32 v[14:15], v[242:243]
	v_pk_mul_f32 v[12:13], v[12:13], v[16:17]
	v_pk_mul_f32 v[16:17], v[20:21], v[10:11] op_sel_hi:[1,0]
	v_cvt_pk_bf16_f32 v12, v12, v13
	v_pk_mul_f32 v[14:15], v[14:15], v[16:17]
	s_nop 0
	v_cvt_pk_bf16_f32 v13, v14, v15
	global_store_dwordx2 v[32:33], v[12:13], off offset:192
	s_waitcnt vmcnt(12)
	v_mov_b64_e32 v[12:13], v[244:245]
	v_mov_b64_e32 v[14:15], v[246:247]
	v_pk_mul_f32 v[8:9], v[8:9], v[12:13]
	v_pk_mul_f32 v[4:5], v[4:5], v[14:15]
	v_cvt_pk_bf16_f32 v8, v8, v9
	v_cvt_pk_bf16_f32 v9, v4, v5
	global_store_dwordx2 v[32:33], v[8:9], off offset:208
	global_load_dwordx4 v[12:15], v1, s[8:9] offset:448
	v_pk_mul_f32 v[4:5], v[6:7], v[10:11] op_sel_hi:[1,0]
	v_pk_mul_f32 v[6:7], v[130:131], v[10:11] op_sel_hi:[1,0]
	s_waitcnt vmcnt(0)
	v_pk_mul_f32 v[4:5], v[4:5], v[12:13]
	v_pk_mul_f32 v[2:3], v[2:3], v[14:15]
	v_cvt_pk_bf16_f32 v4, v4, v5
	v_cvt_pk_bf16_f32 v5, v2, v3
	global_store_dwordx2 v[32:33], v[4:5], off offset:224
	global_load_dwordx4 v[2:5], v1, s[8:9] offset:480
	s_waitcnt vmcnt(0)
	v_pk_mul_f32 v[2:3], v[6:7], v[2:3]
	v_pk_mul_f32 v[6:7], v[30:31], v[10:11] op_sel_hi:[1,0]
	v_cvt_pk_bf16_f32 v2, v2, v3
	v_pk_mul_f32 v[4:5], v[6:7], v[4:5]
	s_nop 0
	v_cvt_pk_bf16_f32 v3, v4, v5
	global_store_dwordx2 v[32:33], v[2:3], off offset:240

; DI float lo16(unsigned u) { return __uint_as_float(u << 16); }
; DI float hi16(unsigned u) { return __uint_as_float(u & 0xffff0000u); }
; DI void combine_phase(const P& p, int l, int ntok) {
;     ...
;   for (int row = gw; row < ntok; row += nw) {
;     int mr = row < T ? (row >> 13) : 4;
;     int4 sl = *(const int4*)(TOKSLOT + row * 4);
;     float4 gt = *(const float4*)(TOKG + row * 4);
;     float xv[16];
; #pragma unroll
;     for (int i = 0; i < 4; ++i) {
;       int c = (i * 64 + lane) * 4;
;       float4 x = *(const float4*)(XA + (size_t)row * D + c);
;       float4 m5 = *(const float4*)(MOD + mr * 6144 + 5 * 1024 + c);
;       uint2 y0 = *(const uint2*)(Y + (size_t)sl.x * 1024 + c), y1 = *(const uint2*)(Y + (size_t)sl.y * 1024 + c);
;       uint2 y2 = *(const uint2*)(Y + (size_t)sl.z * 1024 + c), y3 = *(const uint2*)(Y + (size_t)sl.w * 1024 + c);
;       float a0 = gt.x * lo16(y0.x) + gt.y * lo16(y1.x) + gt.z * lo16(y2.x) + gt.w * lo16(y3.x);
;       float a1 = gt.x * hi16(y0.x) + gt.y * hi16(y1.x) + gt.z * hi16(y2.x) + gt.w * hi16(y3.x);
;       float a2 = gt.x * lo16(y0.y) + gt.y * lo16(y1.y) + gt.z * lo16(y2.y) + gt.w * lo16(y3.y);
;       float a3 = gt.x * hi16(y0.y) + gt.y * hi16(y1.y) + gt.z * hi16(y2.y) + gt.w * hi16(y3.y);
;       xv[4 * i] = x.x + m5.x * a0; xv[4 * i + 1] = x.y + m5.y * a1; xv[4 * i + 2] = x.z + m5.z * a2; xv[4 * i + 3] = x.w + m5.w * a3;
;       float4 o = make_float4(xv[4 * i], xv[4 * i + 1], xv[4 * i + 2], xv[4 * i + 3]);
;       if (l == 1) *(float4*)(p.out + (size_t)row * D + c) = o;
;       else *(float4*)(XA + (size_t)row * D + c) = o;
.LBB0_1538:
	v_min_i32_e32 v2, 0x8000, v18
	v_ashrrev_i32_e32 v41, 31, v40
	v_readlane_b32 s0, v253, 40
	v_ashrrev_i32_e32 v10, 13, v2
	v_lshlrev_b64 v[2:3], 2, v[40:41]
	v_readlane_b32 s1, v253, 41
	v_mul_i32_i24_e32 v56, 0x1800, v10
	v_ashrrev_i32_e32 v57, 31, v56
	v_lshl_add_u64 v[4:5], s[0:1], 0, v[2:3]
	v_readlane_b32 s0, v253, 32
	v_readlane_b32 s1, v253, 33
	v_lshl_add_u64 v[58:59], v[38:39], 0, v[26:27]
	v_readlane_b32 s12, v254, 52
	v_lshl_add_u64 v[2:3], s[0:1], 0, v[2:3]
	global_load_dwordx4 v[6:9], v[2:3], off
	v_lshl_add_u64 v[2:3], v[56:57], 2, s[96:97]
	s_mov_b64 s[0:1], 0x5000
	v_lshl_add_u64 v[60:61], v[2:3], 0, s[0:1]
	global_load_dwordx4 v[2:5], v[4:5], off
	s_mov_b32 s0, 0x2234c000
	v_add_co_u32_e32 v72, vcc, s0, v58
	v_readlane_b32 s13, v254, 53
	s_nop 0
	v_addc_co_u32_e32 v73, vcc, 0, v59, vcc
	s_mov_b64 s[10:11], -1
	s_andn2_b64 vcc, exec, s[12:13]
	s_waitcnt vmcnt(0)
	v_ashrrev_i32_e32 v13, 31, v3
	v_mov_b32_e32 v12, v3
	v_ashrrev_i32_e32 v11, 31, v2
	v_mov_b32_e32 v10, v2
	v_lshlrev_b64 v[2:3], 11, v[12:13]
	v_ashrrev_i32_e32 v13, 31, v4
	v_mov_b32_e32 v12, v4
	v_ashrrev_i32_e32 v15, 31, v5
	v_mov_b32_e32 v14, v5
	v_lshlrev_b64 v[10:11], 11, v[10:11]
	v_lshlrev_b64 v[4:5], 11, v[14:15]
	v_lshlrev_b64 v[12:13], 11, v[12:13]
	v_lshl_add_u64 v[62:63], v[36:37], 0, v[10:11]
	v_lshl_add_u64 v[64:65], v[36:37], 0, v[2:3]
	v_lshl_add_u64 v[66:67], v[36:37], 0, v[12:13]
	v_lshl_add_u64 v[68:69], v[36:37], 0, v[4:5]
	v_lshl_add_u64 v[240:241], v[60:61], 0, v[178:179]
	global_load_dwordx2 v[130:131], v[62:63], off
	global_load_dwordx2 v[132:133], v[64:65], off
	global_load_dwordx2 v[134:135], v[66:67], off
	global_load_dwordx2 v[136:137], v[68:69], off
	global_load_dwordx4 v[180:183], v[72:73], off
	global_load_dwordx4 v[202:205], v[240:241], off
	global_load_dwordx2 v[138:139], v[62:63], off offset:512
	global_load_dwordx2 v[140:141], v[64:65], off offset:512
	global_load_dwordx2 v[142:143], v[66:67], off offset:512
	global_load_dwordx2 v[144:145], v[68:69], off offset:512
	global_load_dwordx4 v[184:187], v[72:73], off offset:1024
	global_load_dwordx4 v[206:209], v[240:241], off offset:1024
	global_load_dwordx2 v[146:147], v[62:63], off offset:1024
	global_load_dwordx2 v[148:149], v[64:65], off offset:1024
	global_load_dwordx2 v[150:151], v[66:67], off offset:1024
	global_load_dwordx2 v[152:153], v[68:69], off offset:1024
	global_load_dwordx4 v[194:197], v[72:73], off offset:2048
	global_load_dwordx4 v[232:235], v[240:241], off offset:2048
	global_load_dwordx2 v[154:155], v[62:63], off offset:1536
	global_load_dwordx2 v[156:157], v[64:65], off offset:1536
	global_load_dwordx2 v[158:159], v[66:67], off offset:1536
	global_load_dwordx2 v[160:161], v[68:69], off offset:1536
	global_load_dwordx4 v[198:201], v[72:73], off offset:3072
	global_load_dwordx4 v[236:239], v[240:241], off offset:3072
	s_waitcnt vmcnt(18)
	v_mov_b64_e32 v[10:11], v[130:131]
	v_mov_b64_e32 v[2:3], v[132:133]
	v_mov_b64_e32 v[12:13], v[134:135]
	v_mov_b64_e32 v[4:5], v[136:137]
	v_lshl_add_u64 v[14:15], v[60:61], 0, v[178:179]
	v_lshlrev_b32_e32 v16, 16, v10
	v_lshlrev_b32_e32 v54, 16, v2
	v_lshlrev_b32_e32 v70, 16, v12
	v_lshlrev_b32_e32 v74, 16, v4
	v_and_b32_e32 v55, 0xffff0000, v10
	v_and_b32_e32 v17, 0xffff0000, v2
	v_and_b32_e32 v71, 0xffff0000, v12
	v_and_b32_e32 v75, 0xffff0000, v4
	v_lshlrev_b32_e32 v76, 16, v11
	v_lshlrev_b32_e32 v78, 16, v3
	v_lshlrev_b32_e32 v80, 16, v13
	v_lshlrev_b32_e32 v82, 16, v5
	v_and_b32_e32 v79, 0xffff0000, v11
	v_and_b32_e32 v77, 0xffff0000, v3
	v_and_b32_e32 v81, 0xffff0000, v13
	v_and_b32_e32 v83, 0xffff0000, v5
	v_mov_b64_e32 v[2:3], v[180:181]
	v_mov_b64_e32 v[4:5], v[182:183]
	v_mov_b64_e32 v[10:11], v[202:203]
	v_mov_b64_e32 v[12:13], v[204:205]
	v_pk_mul_f32 v[16:17], v[6:7], v[16:17]
	v_pk_mul_f32 v[14:15], v[6:7], v[76:77]
	v_pk_fma_f32 v[16:17], v[6:7], v[54:55], v[16:17] op_sel:[1,0,0] op_sel_hi:[0,1,1]
	v_pk_fma_f32 v[14:15], v[6:7], v[78:79], v[14:15] op_sel:[1,0,0] op_sel_hi:[0,1,1]
	v_mov_b32_e32 v76, v9
	v_pk_fma_f32 v[16:17], v[8:9], v[70:71], v[16:17] op_sel_hi:[0,1,1]
	v_pk_fma_f32 v[14:15], v[8:9], v[80:81], v[14:15] op_sel_hi:[0,1,1]
	v_pk_fma_f32 v[16:17], v[76:77], v[74:75], v[16:17] op_sel_hi:[0,1,1]
	v_pk_fma_f32 v[14:15], v[76:77], v[82:83], v[14:15] op_sel_hi:[0,1,1]
	v_lshl_add_u64 v[74:75], v[42:43], 0, v[26:27]
	v_pk_fma_f32 v[2:3], v[10:11], v[16:17], v[2:3]
	v_cndmask_b32_e64 v10, 0, 1, s[12:13]
	v_pk_fma_f32 v[4:5], v[12:13], v[14:15], v[4:5]
	v_cmp_ne_u32_e64 s[0:1], 1, v10
	s_cbranch_vccnz .LBB0_1540
	s_mov_b64 s[10:11], 0
	global_store_dwordx4 v[74:75], v[2:5], off

; DI float lo16(unsigned u) { return __uint_as_float(u << 16); }
; DI float hi16(unsigned u) { return __uint_as_float(u & 0xffff0000u); }
; DI void combine_phase(const P& p, int l, int ntok) {
;     ...
;     for (int i = 0; i < 4; ++i) {
;       int c = (i * 64 + lane) * 4;
;       float4 x = *(const float4*)(XA + (size_t)row * D + c);
;       float4 m5 = *(const float4*)(MOD + mr * 6144 + 5 * 1024 + c);
;       uint2 y0 = *(const uint2*)(Y + (size_t)sl.x * 1024 + c), y1 = *(const uint2*)(Y + (size_t)sl.y * 1024 + c);
;       uint2 y2 = *(const uint2*)(Y + (size_t)sl.z * 1024 + c), y3 = *(const uint2*)(Y + (size_t)sl.w * 1024 + c);
;       float a0 = gt.x * lo16(y0.x) + gt.y * lo16(y1.x) + gt.z * lo16(y2.x) + gt.w * lo16(y3.x);
;       float a1 = gt.x * hi16(y0.x) + gt.y * hi16(y1.x) + gt.z * hi16(y2.x) + gt.w * hi16(y3.x);
;       float a2 = gt.x * lo16(y0.y) + gt.y * lo16(y1.y) + gt.z * lo16(y2.y) + gt.w * lo16(y3.y);
;       float a3 = gt.x * hi16(y0.y) + gt.y * hi16(y1.y) + gt.z * hi16(y2.y) + gt.w * hi16(y3.y);
;       xv[4 * i] = x.x + m5.x * a0; xv[4 * i + 1] = x.y + m5.y * a1; xv[4 * i + 2] = x.z + m5.z * a2; xv[4 * i + 3] = x.w + m5.w * a3;
;       float4 o = make_float4(xv[4 * i], xv[4 * i + 1], xv[4 * i + 2], xv[4 * i + 3]);
;       if (l == 1) *(float4*)(p.out + (size_t)row * D + c) = o;
;       else *(float4*)(XA + (size_t)row * D + c) = o;
.LBB0_1542:
	s_waitcnt vmcnt(13)
	v_mov_b64_e32 v[10:11], v[138:139]
	s_nop 0
	v_mov_b64_e32 v[12:13], v[140:141]
	v_mov_b64_e32 v[16:17], v[142:143]
	v_mov_b64_e32 v[70:71], v[144:145]
	v_lshlrev_b32_e32 v54, 2, v20
	v_mov_b32_e32 v55, v179
	v_lshl_add_u64 v[14:15], v[60:61], 0, v[54:55]
	v_pk_mov_b32 v[78:79], v[6:7], v[6:7] op_sel:[1,0]
	v_mov_b32_e32 v76, v8
	v_mov_b32_e32 v77, v8
	v_mov_b32_e32 v8, v9
	s_mov_b64 s[10:11], -1
	s_and_b64 vcc, exec, s[0:1]
	v_lshlrev_b32_e32 v80, 16, v10
	v_lshlrev_b32_e32 v82, 16, v12
	v_lshlrev_b32_e32 v84, 16, v16
	v_and_b32_e32 v83, 0xffff0000, v10
	v_and_b32_e32 v81, 0xffff0000, v12
	v_and_b32_e32 v85, 0xffff0000, v16
	v_lshlrev_b32_e32 v88, 16, v11
	v_lshlrev_b32_e32 v90, 16, v13
	v_lshlrev_b32_e32 v92, 16, v17
	v_and_b32_e32 v91, 0xffff0000, v11
	v_and_b32_e32 v89, 0xffff0000, v13
	v_and_b32_e32 v93, 0xffff0000, v17
	v_mov_b64_e32 v[10:11], v[184:185]
	v_mov_b64_e32 v[12:13], v[186:187]
	s_nop 0
	v_mov_b64_e32 v[14:15], v[206:207]
	v_mov_b64_e32 v[16:17], v[208:209]
	v_pk_mul_f32 v[80:81], v[6:7], v[80:81]
	v_lshlrev_b32_e32 v86, 16, v70
	v_pk_fma_f32 v[80:81], v[78:79], v[82:83], v[80:81]
	v_and_b32_e32 v87, 0xffff0000, v70
	v_pk_fma_f32 v[80:81], v[76:77], v[84:85], v[80:81]
	v_lshlrev_b32_e32 v70, 16, v71
	v_pk_fma_f32 v[80:81], v[8:9], v[86:87], v[80:81]
	v_and_b32_e32 v71, 0xffff0000, v71
	v_pk_fma_f32 v[10:11], v[14:15], v[80:81], v[10:11]
	v_pk_mul_f32 v[14:15], v[6:7], v[88:89]
	s_nop 0
	v_pk_fma_f32 v[14:15], v[78:79], v[90:91], v[14:15]
	s_nop 0
	v_pk_fma_f32 v[14:15], v[76:77], v[92:93], v[14:15]
	s_nop 0
	v_pk_fma_f32 v[14:15], v[8:9], v[70:71], v[14:15]
	s_nop 0
	v_pk_fma_f32 v[12:13], v[16:17], v[14:15], v[12:13]
	s_cbranch_vccnz .LBB0_1544
	s_mov_b64 s[10:11], 0
	global_store_dwordx4 v[74:75], v[10:13], off offset:1024

; DI float lo16(unsigned u) { return __uint_as_float(u << 16); }
; DI float hi16(unsigned u) { return __uint_as_float(u & 0xffff0000u); }
; DI void combine_phase(const P& p, int l, int ntok) {
;     ...
;     for (int i = 0; i < 4; ++i) {
;       int c = (i * 64 + lane) * 4;
;       float4 x = *(const float4*)(XA + (size_t)row * D + c);
;       float4 m5 = *(const float4*)(MOD + mr * 6144 + 5 * 1024 + c);
;       uint2 y0 = *(const uint2*)(Y + (size_t)sl.x * 1024 + c), y1 = *(const uint2*)(Y + (size_t)sl.y * 1024 + c);
;       uint2 y2 = *(const uint2*)(Y + (size_t)sl.z * 1024 + c), y3 = *(const uint2*)(Y + (size_t)sl.w * 1024 + c);
;       float a0 = gt.x * lo16(y0.x) + gt.y * lo16(y1.x) + gt.z * lo16(y2.x) + gt.w * lo16(y3.x);
;       float a1 = gt.x * hi16(y0.x) + gt.y * hi16(y1.x) + gt.z * hi16(y2.x) + gt.w * hi16(y3.x);
;       float a2 = gt.x * lo16(y0.y) + gt.y * lo16(y1.y) + gt.z * lo16(y2.y) + gt.w * lo16(y3.y);
;       float a3 = gt.x * hi16(y0.y) + gt.y * hi16(y1.y) + gt.z * hi16(y2.y) + gt.w * hi16(y3.y);
;       xv[4 * i] = x.x + m5.x * a0; xv[4 * i + 1] = x.y + m5.y * a1; xv[4 * i + 2] = x.z + m5.z * a2; xv[4 * i + 3] = x.w + m5.w * a3;
;       float4 o = make_float4(xv[4 * i], xv[4 * i + 1], xv[4 * i + 2], xv[4 * i + 3]);
;       if (l == 1) *(float4*)(p.out + (size_t)row * D + c) = o;
;       else *(float4*)(XA + (size_t)row * D + c) = o;
.LBB0_1546:
	s_waitcnt vmcnt(8)
	v_mov_b64_e32 v[14:15], v[146:147]
	s_nop 0
	v_mov_b64_e32 v[16:17], v[148:149]
	v_mov_b64_e32 v[82:83], v[150:151]
	v_mov_b64_e32 v[84:85], v[152:153]
	v_lshlrev_b32_e32 v70, 2, v22
	v_mov_b32_e32 v71, v179
	v_lshl_add_u64 v[80:81], v[60:61], 0, v[70:71]
	s_mov_b64 s[10:11], -1
	s_and_b64 vcc, exec, s[0:1]
	v_lshlrev_b32_e32 v86, 16, v14
	v_lshlrev_b32_e32 v88, 16, v16
	v_lshlrev_b32_e32 v90, 16, v82
	v_and_b32_e32 v89, 0xffff0000, v14
	v_and_b32_e32 v87, 0xffff0000, v16
	v_and_b32_e32 v91, 0xffff0000, v82
	v_lshlrev_b32_e32 v94, 16, v15
	v_lshlrev_b32_e32 v96, 16, v17
	v_lshlrev_b32_e32 v98, 16, v83
	v_and_b32_e32 v97, 0xffff0000, v15
	v_and_b32_e32 v95, 0xffff0000, v17
	v_and_b32_e32 v99, 0xffff0000, v83
	v_mov_b64_e32 v[14:15], v[194:195]
	v_mov_b64_e32 v[16:17], v[196:197]
	s_nop 0
	v_mov_b64_e32 v[80:81], v[232:233]
	v_mov_b64_e32 v[82:83], v[234:235]
	v_pk_mul_f32 v[86:87], v[6:7], v[86:87]
	v_lshlrev_b32_e32 v92, 16, v84
	v_pk_fma_f32 v[86:87], v[78:79], v[88:89], v[86:87]
	v_and_b32_e32 v93, 0xffff0000, v84
	v_pk_fma_f32 v[86:87], v[76:77], v[90:91], v[86:87]
	v_lshlrev_b32_e32 v84, 16, v85
	v_pk_fma_f32 v[86:87], v[8:9], v[92:93], v[86:87]
	v_and_b32_e32 v85, 0xffff0000, v85
	v_pk_fma_f32 v[14:15], v[80:81], v[86:87], v[14:15]
	v_pk_mul_f32 v[80:81], v[6:7], v[94:95]
	s_nop 0
	v_pk_fma_f32 v[80:81], v[78:79], v[96:97], v[80:81]
	s_nop 0
	v_pk_fma_f32 v[80:81], v[76:77], v[98:99], v[80:81]
	s_nop 0
	v_pk_fma_f32 v[80:81], v[8:9], v[84:85], v[80:81]
	s_nop 0
	v_pk_fma_f32 v[16:17], v[82:83], v[80:81], v[16:17]
	s_cbranch_vccnz .LBB0_1548
	s_mov_b64 s[10:11], 0
	global_store_dwordx4 v[74:75], v[14:17], off offset:2048

; DI float lo16(unsigned u) { return __uint_as_float(u << 16); }
; DI float hi16(unsigned u) { return __uint_as_float(u & 0xffff0000u); }
; DI void combine_phase(const P& p, int l, int ntok) {
;     ...
;     for (int i = 0; i < 4; ++i) {
;       int c = (i * 64 + lane) * 4;
;       float4 x = *(const float4*)(XA + (size_t)row * D + c);
;       float4 m5 = *(const float4*)(MOD + mr * 6144 + 5 * 1024 + c);
;       uint2 y0 = *(const uint2*)(Y + (size_t)sl.x * 1024 + c), y1 = *(const uint2*)(Y + (size_t)sl.y * 1024 + c);
;       uint2 y2 = *(const uint2*)(Y + (size_t)sl.z * 1024 + c), y3 = *(const uint2*)(Y + (size_t)sl.w * 1024 + c);
;       float a0 = gt.x * lo16(y0.x) + gt.y * lo16(y1.x) + gt.z * lo16(y2.x) + gt.w * lo16(y3.x);
;       float a1 = gt.x * hi16(y0.x) + gt.y * hi16(y1.x) + gt.z * hi16(y2.x) + gt.w * hi16(y3.x);
;       float a2 = gt.x * lo16(y0.y) + gt.y * lo16(y1.y) + gt.z * lo16(y2.y) + gt.w * lo16(y3.y);
;       float a3 = gt.x * hi16(y0.y) + gt.y * hi16(y1.y) + gt.z * hi16(y2.y) + gt.w * hi16(y3.y);
;       xv[4 * i] = x.x + m5.x * a0; xv[4 * i + 1] = x.y + m5.y * a1; xv[4 * i + 2] = x.z + m5.z * a2; xv[4 * i + 3] = x.w + m5.w * a3;
;       float4 o = make_float4(xv[4 * i], xv[4 * i + 1], xv[4 * i + 2], xv[4 * i + 3]);
;       if (l == 1) *(float4*)(p.out + (size_t)row * D + c) = o;
;       else *(float4*)(XA + (size_t)row * D + c) = o;
.LBB0_1550:
	s_waitcnt vmcnt(3)
	v_mov_b64_e32 v[84:85], v[154:155]
	v_mov_b64_e32 v[86:87], v[156:157]
	v_mov_b64_e32 v[88:89], v[158:159]
	s_nop 0
	v_mov_b64_e32 v[68:69], v[160:161]
	v_lshlrev_b32_e32 v62, 2, v24
	v_mov_b32_e32 v63, v179
	v_lshl_add_u64 v[60:61], v[60:61], 0, v[62:63]
	v_mov_b64_e32 v[64:65], v[198:199]
	v_mov_b64_e32 v[66:67], v[200:201]
	v_mov_b64_e32 v[80:81], v[236:237]
	v_mov_b64_e32 v[82:83], v[238:239]
	s_and_b64 vcc, exec, s[0:1]
	s_mov_b64 s[0:1], -1
	v_lshlrev_b32_e32 v60, 16, v84
	v_and_b32_e32 v73, 0xffff0000, v84
	v_and_b32_e32 v61, 0xffff0000, v86
	v_lshlrev_b32_e32 v84, 16, v85
	v_and_b32_e32 v95, 0xffff0000, v85
	v_and_b32_e32 v85, 0xffff0000, v87
	v_lshlrev_b32_e32 v72, 16, v86
	v_lshlrev_b32_e32 v94, 16, v87
	v_pk_mul_f32 v[60:61], v[6:7], v[60:61]
	v_pk_mul_f32 v[6:7], v[6:7], v[84:85]
	v_lshlrev_b32_e32 v90, 16, v88
	v_and_b32_e32 v91, 0xffff0000, v88
	v_lshlrev_b32_e32 v86, 16, v89
	v_and_b32_e32 v87, 0xffff0000, v89
	v_pk_fma_f32 v[60:61], v[78:79], v[72:73], v[60:61]
	v_pk_fma_f32 v[6:7], v[78:79], v[94:95], v[6:7]
	v_lshlrev_b32_e32 v92, 16, v68
	v_and_b32_e32 v93, 0xffff0000, v68
	v_lshlrev_b32_e32 v68, 16, v69
	v_and_b32_e32 v69, 0xffff0000, v69
	v_pk_fma_f32 v[60:61], v[76:77], v[90:91], v[60:61]
	v_pk_fma_f32 v[6:7], v[76:77], v[86:87], v[6:7]
	v_pk_fma_f32 v[60:61], v[8:9], v[92:93], v[60:61]
	v_pk_fma_f32 v[8:9], v[8:9], v[68:69], v[6:7]
	v_pk_fma_f32 v[6:7], v[80:81], v[60:61], v[64:65]
	v_pk_fma_f32 v[8:9], v[82:83], v[8:9], v[66:67]
	s_cbranch_vccnz .LBB0_1552
	s_mov_b64 s[0:1], 0
	global_store_dwordx4 v[74:75], v[6:9], off offset:3072
